# prep: loop-invariant small index products use the full-rate 24-bit multiply (v_mul_u32_u24) instead of v_mul_lo_u32 (15 sites, operands < 2^10)
# speedup vs baseline: 1.0270x; 1.0056x over previous
; __device__ __forceinline__ unsigned pk_bf16(float lo, float hi) { const f32x2 v = (f32x2){lo, hi}; const bf16v2 b = __builtin_convertvector(v, bf16v2); return __builtin_bit_cast(unsigned, b); }
; __device__ __forceinline__ float bf_lo(unsigned u) { return __uint_as_float(u << 16); }
; __device__ __forceinline__ float bf_hi(unsigned u) { return __uint_as_float(u & 0xffff0000u); }
; #define LDS_BARRIER() do { asm volatile("s_waitcnt lgkmcnt(0)" ::: "memory"); __builtin_amdgcn_s_barrier(); asm volatile("" ::: "memory"); } while (0)
; __device__ __forceinline__ void phase_prep(const Params& p, unsigned char* shm) {
;     ...
;             const int nitem = item + (int)gridDim.x;
;             zload(nitem < NCH * 16 ? nitem : item);
;         }
;         LDS_BARRIER();
;         {
;             const int j = tid >> 3, p8 = tid & 7;
; #pragma unroll
;             for (int isa = 0; isa < 2; ++isa) {
;                 const int c = isa * 64 + 8 * p8;
;                 const u32x4 cu = *(const u32x4*)(zh + (j + 1) * LZH + c), pu = *(const u32x4*)(zh + j * LZH + c);
;                 const f32x4 m0 = *(const f32x4*)(prm + 512 + c), m1 = *(const f32x4*)(prm + 512 + c + 4);
;                 const unsigned cw[4] = {cu.x, cu.y, cu.z, cu.w}, pw[4] = {pu.x, pu.y, pu.z, pu.w};
;                 float x[8];
; #pragma unroll
;                 for (int e = 0; e < 4; ++e) { const float c0 = bf_lo(cw[e]), c1 = bf_hi(cw[e]), mA = e < 2 ? m0[2 * e] : m1[2 * e - 4], mB = e < 2 ? m0[2 * e + 1] : m1[2 * e - 3];
;                     x[2 * e] = c0 + mA * (bf_lo(pw[e]) - c0); x[2 * e + 1] = c1 + mB * (bf_hi(pw[e]) - c1); }
;                 if (isa == 0) {
; #pragma unroll
;                     for (int e = 0; e < 4; ++e) { const f32x2 th = tanh2((f32x2){x[2 * e], x[2 * e + 1]}); x[2 * e] = th.x; x[2 * e + 1] = th.y; }
;                 }
;                 *(u32x4*)((isa ? tha : thw) + j * LD + 8 * p8) = (u32x4){pk_bf16(x[0], x[1]), pk_bf16(x[2], x[3]), pk_bf16(x[4], x[5]), pk_bf16(x[6], x[7])};
.LBB0_189:
	s_or_b64 exec, exec, s[18:19]
	s_add_i32 s70, s26, s38
	s_cmpk_gt_i32 s70, 0x21ff
	s_cselect_b64 s[42:43], -1, 0
	s_cmpk_lt_i32 s70, 0x2200
	s_cselect_b32 s18, s70, s26
	s_mov_b64 s[20:21], s[88:89]
	s_lshl_b32 s18, s18, 2
	s_andn2_b32 s18, s18, 63
	s_add_i32 s22, s18, -1
	v_add_u32_e32 v0, s22, v123
	v_max_i32_e32 v0, 0, v0
	s_mov_b64 s[18:19], s[90:91]
	s_waitcnt vmcnt(6) lgkmcnt(0)
	v_mov_b64_e32 v[8:9], s[20:21]
	v_mad_u64_u32 v[0:1], s[20:21], v0, s3, v[8:9]
	v_lshlrev_b32_e32 v126, 1, v122
	v_add_u32_e32 v2, s22, v176
	v_lshl_add_u64 v[0:1], v[0:1], 0, v[126:127]
	v_max_i32_e32 v2, 0, v2
	v_add_co_u32_e32 v0, vcc, s49, v0
	v_mad_u64_u32 v[2:3], s[20:21], v2, s3, v[8:9]
	v_mov_b32_e32 v137, v127
	v_addc_co_u32_e32 v1, vcc, 0, v1, vcc
	v_lshl_add_u64 v[2:3], v[2:3], 0, v[136:137]
	v_add_co_u32_e32 v2, vcc, s49, v2
	v_mov_b32_e32 v139, v127
	s_nop 0
	v_addc_co_u32_e32 v3, vcc, 0, v3, vcc
	global_load_dwordx4 v[20:23], v[0:1], off offset:2048
	global_load_dwordx4 v[16:19], v[2:3], off offset:2048
	v_add_u32_e32 v0, s22, v121
	v_max_i32_e32 v0, 0, v0
	v_mad_u64_u32 v[0:1], s[20:21], v0, s3, v[8:9]
	v_add_u32_e32 v2, s22, v175
	v_lshl_add_u64 v[0:1], v[124:125], 1, v[0:1]
	v_max_i32_e32 v2, 0, v2
	v_add_co_u32_e32 v0, vcc, s49, v0
	v_mad_u64_u32 v[2:3], s[20:21], v2, s3, v[8:9]
	v_add_u32_sdwa v10, s22, v157 dst_sel:DWORD dst_unused:UNUSED_PAD src0_sel:DWORD src1_sel:WORD_1
	v_addc_co_u32_e32 v1, vcc, 0, v1, vcc
	v_lshl_add_u64 v[2:3], v[2:3], 0, v[138:139]
	v_max_i32_e32 v10, 0, v10
	v_add_co_u32_e32 v2, vcc, s49, v2
	v_mad_u64_u32 v[10:11], s[20:21], v10, s3, v[8:9]
	v_mov_b32_e32 v141, v127
	v_add_u32_sdwa v12, s22, v174 dst_sel:DWORD dst_unused:UNUSED_PAD src0_sel:DWORD src1_sel:WORD_1
	v_addc_co_u32_e32 v3, vcc, 0, v3, vcc
	v_lshl_add_u64 v[10:11], v[10:11], 0, v[140:141]
	v_max_i32_e32 v12, 0, v12
	v_add_co_u32_e32 v10, vcc, s49, v10
	v_mad_u64_u32 v[8:9], s[20:21], v12, s3, v[8:9]
	v_mov_b32_e32 v143, v127
	v_lshlrev_b32_e32 v188, 3, v187
	v_addc_co_u32_e32 v11, vcc, 0, v11, vcc
	v_lshl_add_u64 v[8:9], v[8:9], 0, v[142:143]
	v_ashrrev_i32_e32 v186, 3, v187
	v_and_b32_e32 v32, 56, v188
	v_add_co_u32_e32 v8, vcc, s49, v8
	v_mul_u32_u24_e32 v24, s48, v186
	s_nop 0
	v_addc_co_u32_e32 v9, vcc, 0, v9, vcc
	v_lshlrev_b32_e32 v144, 1, v32
	global_load_dwordx4 v[4:7], v[0:1], off offset:2048
	s_nop 0
	global_load_dwordx4 v[0:3], v[2:3], off offset:2048
	s_nop 0
	global_load_dwordx4 v[12:15], v[10:11], off offset:2048
	s_nop 0
	global_load_dwordx4 v[8:11], v[8:9], off offset:2048
	s_waitcnt lgkmcnt(0)
	s_barrier
	v_add3_u32 v45, 0, v24, v144
	ds_read_b128 v[24:27], v45 offset:37136
	ds_read_b128 v[28:31], v45 offset:36864
	v_lshlrev_b32_e32 v46, 2, v32
	v_add_u32_e32 v32, 0, v46
	v_add_u32_e32 v47, 0x25000, v32
	ds_read_b128 v[32:35], v47
	ds_read_b128 v[36:39], v47 offset:16
	s_waitcnt lgkmcnt(3)
	v_lshlrev_b32_e32 v40, 16, v24
	v_and_b32_e32 v41, 0xffff0000, v24
	s_waitcnt lgkmcnt(2)
	v_lshlrev_b32_e32 v42, 16, v28
	v_and_b32_e32 v43, 0xffff0000, v28
	v_lshlrev_b32_e32 v24, 16, v25
	v_and_b32_e32 v25, 0xffff0000, v25
	v_lshlrev_b32_e32 v28, 16, v29
	v_and_b32_e32 v29, 0xffff0000, v29
	v_pk_add_f32 v[28:29], v[28:29], v[24:25] neg_lo:[0,1] neg_hi:[0,1]
	v_pk_add_f32 v[42:43], v[42:43], v[40:41] neg_lo:[0,1] neg_hi:[0,1]
	s_waitcnt lgkmcnt(1)
	v_pk_fma_f32 v[24:25], v[34:35], v[28:29], v[24:25]
	v_lshlrev_b32_e32 v28, 16, v26
	v_and_b32_e32 v29, 0xffff0000, v26
	v_lshlrev_b32_e32 v34, 16, v30
	v_and_b32_e32 v35, 0xffff0000, v30
	v_lshlrev_b32_e32 v26, 16, v27
	v_and_b32_e32 v27, 0xffff0000, v27
	v_lshlrev_b32_e32 v30, 16, v31
	v_and_b32_e32 v31, 0xffff0000, v31
	v_pk_add_f32 v[34:35], v[34:35], v[28:29] neg_lo:[0,1] neg_hi:[0,1]
	v_pk_add_f32 v[30:31], v[30:31], v[26:27] neg_lo:[0,1] neg_hi:[0,1]
	v_pk_fma_f32 v[32:33], v[32:33], v[42:43], v[40:41]
	s_waitcnt lgkmcnt(0)
	v_pk_fma_f32 v[28:29], v[36:37], v[34:35], v[28:29]
	v_pk_fma_f32 v[26:27], v[38:39], v[30:31], v[26:27]
	v_pk_mul_f32 v[32:33], v[32:33], s[2:3] op_sel_hi:[1,0]
	v_pk_mul_f32 v[24:25], v[24:25], s[2:3] op_sel_hi:[1,0]
	v_pk_mul_f32 v[28:29], v[28:29], s[2:3] op_sel_hi:[1,0]
	v_pk_mul_f32 v[26:27], v[26:27], s[2:3] op_sel_hi:[1,0]
	v_exp_f32_e32 v32, v32
	v_exp_f32_e32 v33, v33
	v_exp_f32_e32 v24, v24
	v_exp_f32_e32 v25, v25
	v_exp_f32_e32 v28, v28
	v_exp_f32_e32 v29, v29
	v_exp_f32_e32 v26, v26
	v_exp_f32_e32 v27, v27
	v_pk_add_f32 v[32:33], v[32:33], 1.0 op_sel_hi:[1,0]
	v_pk_add_f32 v[24:25], v[24:25], 1.0 op_sel_hi:[1,0]
	v_pk_add_f32 v[28:29], v[28:29], 1.0 op_sel_hi:[1,0]
	v_pk_add_f32 v[26:27], v[26:27], 1.0 op_sel_hi:[1,0]
	v_rcp_f32_e32 v32, v32
	v_rcp_f32_e32 v33, v33
	v_rcp_f32_e32 v24, v24
	v_rcp_f32_e32 v25, v25
	v_rcp_f32_e32 v28, v28
	v_rcp_f32_e32 v29, v29
	v_rcp_f32_e32 v26, v26
	v_rcp_f32_e32 v27, v27
	v_mul_u32_u24_e32 v44, s50, v186
	v_pk_fma_f32 v[30:31], v[32:33], 2.0, 1.0 op_sel_hi:[1,0,0] neg_lo:[1,0,0] neg_hi:[1,0,0]
	v_pk_fma_f32 v[32:33], v[24:25], 2.0, 1.0 op_sel_hi:[1,0,0] neg_lo:[1,0,0] neg_hi:[1,0,0]
	v_pk_fma_f32 v[28:29], v[28:29], 2.0, 1.0 op_sel_hi:[1,0,0] neg_lo:[1,0,0] neg_hi:[1,0,0]
	v_pk_fma_f32 v[34:35], v[26:27], 2.0, 1.0 op_sel_hi:[1,0,0] neg_lo:[1,0,0] neg_hi:[1,0,0]
	v_cvt_pk_bf16_f32 v24, v30, v31
	v_cvt_pk_bf16_f32 v25, v32, v33
	v_cvt_pk_bf16_f32 v26, v28, v29
	v_cvt_pk_bf16_f32 v27, v34, v35
	v_add3_u32 v44, 0, v44, v144
	ds_read_b128 v[28:31], v45 offset:37264
	ds_write_b128 v44, v[24:27]
	ds_read_b128 v[24:27], v45 offset:36992
	ds_read_b128 v[32:35], v47 offset:256
	ds_read_b128 v[36:39], v47 offset:272
	s_and_b32 s22, s26, 15
	s_lshl_b32 s40, s22, 7
	s_waitcnt lgkmcnt(4)
; __device__ __forceinline__ float bf_lo(unsigned u) { return __uint_as_float(u << 16); }
; __device__ __forceinline__ void phase_prep(const Params& p, unsigned char* shm) {
;     ...
;                 if (isa == 0) {
; #pragma unroll
;                     for (int e = 0; e < 4; ++e) { const f32x2 th = tanh2((f32x2){x[2 * e], x[2 * e + 1]}); x[2 * e] = th.x; x[2 * e + 1] = th.y; }
;                 }
;                 *(u32x4*)((isa ? tha : thw) + j * LD + 8 * p8) = (u32x4){pk_bf16(x[0], x[1]), pk_bf16(x[2], x[3]), pk_bf16(x[4], x[5]), pk_bf16(x[6], x[7])};
;             }
;             {
;                 const u32x4 cu = *(const u32x4*)(zs + (j + 1) * LZS + 128 + 8 * p8), pu = *(const u32x4*)(zs + j * LZS + 128 + 8 * p8);
;                 const f32x4 m0 = *(const f32x4*)(prm + 256 + 8 * p8), m1 = *(const f32x4*)(prm + 256 + 8 * p8 + 4);
;                 const unsigned cw[4] = {cu.x, cu.y, cu.z, cu.w}, pw[4] = {pu.x, pu.y, pu.z, pu.w};
;                 float x[8];
; #pragma unroll
;                 for (int e = 0; e < 4; ++e) { const float c0 = bf_lo(cw[e]), c1 = bf_hi(cw[e]), mA = e < 2 ? m0[2 * e] : m1[2 * e - 4], mB = e < 2 ? m0[2 * e + 1] : m1[2 * e - 3];
;                     x[2 * e] = c0 + mA * (bf_lo(pw[e]) - c0); x[2 * e + 1] = c1 + mB * (bf_hi(pw[e]) - c1); }
;                 *(u32x4*)(p.PV + ((size_t)(row0 + j) * 16 + h) * 64 + 8 * p8) = (u32x4){pk_bf16(x[0], x[1]), pk_bf16(x[2], x[3]), pk_bf16(x[4], x[5]), pk_bf16(x[6], x[7])};
;             }
;         }
;         LDS_BARRIER();
;         const int tt = wid & 3, chh = wid >> 2, tk = 16 * tt + fr, row = row0 + tk;
;         f32x4 lw[2], av[2], vm[2], kkv[2], kp[2], rm[2], cs[2]; float nrm = 0.f, rk = 0.f;
;         {
;             f32x4 accd[2], acca[2];
; #pragma unroll
;             for (int n = 0; n < 2; ++n) { accd[n] = (f32x4){0.f, 0.f, 0.f, 0.f}; acca[n] = (f32x4){0.f, 0.f, 0.f, 0.f}; }
; #pragma unroll
;             for (int ks = 0; ks < 2; ++ks) {
;                 const bf16x8 bw = ldfrag(thw, LD, 16 * tt, 32 * ks, fr, fq), ba = ldfrag(tha, LD, 16 * tt, 32 * ks, fr, fq);
; #pragma unroll
;                 for (int n = 0; n < 2; ++n) {
;                     accd[n] = MFMA16(ldfrag(w2P, LD, 32 * chh + 16 * n, 32 * ks, fr, fq), bw, accd[n]);
;                     acca[n] = MFMA16(ldfrag(a2P, LD, 32 * chh + 16 * n, 32 * ks, fr, fq), ba, acca[n]);
;                 }
;             }
	v_lshlrev_b32_e32 v40, 16, v28
	v_and_b32_e32 v41, 0xffff0000, v28
	s_waitcnt lgkmcnt(2)
	v_lshlrev_b32_e32 v42, 16, v24
	v_and_b32_e32 v43, 0xffff0000, v24
	v_lshlrev_b32_e32 v28, 16, v29
	v_and_b32_e32 v29, 0xffff0000, v29
	v_lshlrev_b32_e32 v24, 16, v25
	v_and_b32_e32 v25, 0xffff0000, v25
	v_pk_add_f32 v[24:25], v[24:25], v[28:29] neg_lo:[0,1] neg_hi:[0,1]
	v_pk_add_f32 v[42:43], v[42:43], v[40:41] neg_lo:[0,1] neg_hi:[0,1]
	s_waitcnt lgkmcnt(1)
	v_pk_fma_f32 v[28:29], v[34:35], v[24:25], v[28:29]
	v_lshlrev_b32_e32 v24, 16, v30
	v_and_b32_e32 v25, 0xffff0000, v30
	v_lshlrev_b32_e32 v34, 16, v26
	v_and_b32_e32 v35, 0xffff0000, v26
	v_pk_add_f32 v[34:35], v[34:35], v[24:25] neg_lo:[0,1] neg_hi:[0,1]
	v_lshlrev_b32_e32 v26, 16, v27
	s_waitcnt lgkmcnt(0)
	v_pk_fma_f32 v[34:35], v[36:37], v[34:35], v[24:25]
	v_lshlrev_b32_e32 v24, 16, v31
	v_and_b32_e32 v25, 0xffff0000, v31
	v_and_b32_e32 v27, 0xffff0000, v27
	v_pk_add_f32 v[26:27], v[26:27], v[24:25] neg_lo:[0,1] neg_hi:[0,1]
	v_pk_fma_f32 v[32:33], v[32:33], v[42:43], v[40:41]
	v_pk_fma_f32 v[30:31], v[38:39], v[26:27], v[24:25]
	v_cvt_pk_bf16_f32 v24, v32, v33
	v_cvt_pk_bf16_f32 v25, v28, v29
	v_cvt_pk_bf16_f32 v26, v34, v35
	v_cvt_pk_bf16_f32 v27, v30, v31
	ds_write_b128 v44, v[24:27] offset:9216
	v_mul_u32_u24_e32 v24, s51, v186
	v_add3_u32 v28, 0, v24, v144
	ds_read_b128 v[24:27], v28 offset:55200
	ds_read_b128 v[28:31], v28 offset:54800
	v_add_u32_e32 v36, s52, v46
	ds_read_b128 v[32:35], v36
	ds_read_b128 v[36:39], v36 offset:16
	v_mov_b32_e32 v145, v127
	s_waitcnt lgkmcnt(3)
	v_lshlrev_b32_e32 v40, 16, v24
	v_and_b32_e32 v41, 0xffff0000, v24
	s_waitcnt lgkmcnt(2)
	v_lshlrev_b32_e32 v42, 16, v28
	v_and_b32_e32 v43, 0xffff0000, v28
	v_lshlrev_b32_e32 v24, 16, v25
	v_and_b32_e32 v25, 0xffff0000, v25
	v_lshlrev_b32_e32 v28, 16, v29
	v_and_b32_e32 v29, 0xffff0000, v29
	v_pk_add_f32 v[28:29], v[28:29], v[24:25] neg_lo:[0,1] neg_hi:[0,1]
	v_pk_add_f32 v[42:43], v[42:43], v[40:41] neg_lo:[0,1] neg_hi:[0,1]
	s_waitcnt lgkmcnt(1)
	v_pk_fma_f32 v[28:29], v[34:35], v[28:29], v[24:25]
	v_lshlrev_b32_e32 v24, 16, v26
	v_and_b32_e32 v25, 0xffff0000, v26
	v_lshlrev_b32_e32 v34, 16, v30
	v_and_b32_e32 v35, 0xffff0000, v30
	v_pk_add_f32 v[34:35], v[34:35], v[24:25] neg_lo:[0,1] neg_hi:[0,1]
	v_lshlrev_b32_e32 v26, 16, v31
	s_waitcnt lgkmcnt(0)
	v_pk_fma_f32 v[34:35], v[36:37], v[34:35], v[24:25]
	v_lshlrev_b32_e32 v24, 16, v27
	v_and_b32_e32 v25, 0xffff0000, v27
	v_and_b32_e32 v27, 0xffff0000, v31
	v_pk_add_f32 v[26:27], v[26:27], v[24:25] neg_lo:[0,1] neg_hi:[0,1]
	v_pk_fma_f32 v[32:33], v[32:33], v[42:43], v[40:41]
	v_pk_fma_f32 v[30:31], v[38:39], v[26:27], v[24:25]
	v_cvt_pk_bf16_f32 v25, v28, v29
	v_add_u32_e32 v28, s24, v186
	v_ashrrev_i32_e32 v29, 31, v28
	v_lshlrev_b64 v[28:29], 11, v[28:29]
	v_lshl_add_u64 v[28:29], s[18:19], 0, v[28:29]
	v_lshl_add_u64 v[28:29], v[28:29], 0, s[40:41]
	s_ashr_i32 s29, s25, 8
	v_and_b32_e32 v185, 15, v187
	v_cvt_pk_bf16_f32 v24, v32, v33
	v_cvt_pk_bf16_f32 v26, v34, v35
	v_cvt_pk_bf16_f32 v27, v30, v31
	v_lshl_add_u64 v[28:29], v[28:29], 0, v[144:145]
	s_lshl_b32 s18, s29, 5
	global_store_dwordx4 v[28:29], v[24:27], off
	v_and_b32_e32 v141, 48, v187
	s_waitcnt lgkmcnt(0)
	s_barrier
	v_or_b32_e32 v24, s18, v185
	v_mul_u32_u24_e32 v145, s50, v24
	v_add3_u32 v60, s5, v141, v145
	s_bfe_u32 s28, s25, 0x20006
	ds_read_b128 v[24:27], v60
	v_lshl_or_b32 v126, s28, 4, v185
	v_mad_u32_u24 v143, v126, s50, 0
	v_add_u32_e32 v189, v143, v141
	v_add3_u32 v64, s7, v141, v145
	ds_read_b128 v[28:31], v189
	ds_read_b128 v[32:35], v64
	ds_read_b128 v[36:39], v189 offset:64
	ds_read_b128 v[40:43], v60 offset:64
	ds_read_b128 v[44:47], v189 offset:9216
	ds_read_b128 v[48:51], v189 offset:9280
	ds_read_b128 v[52:55], v64 offset:64
	ds_read_b128 v[56:59], v60 offset:2304
	ds_read_b128 v[60:63], v60 offset:2368
	s_waitcnt lgkmcnt(4)
	v_mfma_f32_16x16x32_bf16 v[32:35], v[32:35], v[44:47], 0
	v_bfe_u32 v137, v187, 4, 2
	v_lshlrev_b32_e32 v139, 2, v137
	v_or_b32_e32 v146, s18, v139
	v_mfma_f32_16x16x32_bf16 v[24:27], v[24:27], v[28:31], 0
	v_lshlrev_b32_e32 v147, 1, v146
	s_lshl_b32 s20, s28, 8
	s_add_i32 s20, s20, 0
	s_waitcnt lgkmcnt(1)
	v_mfma_f32_16x16x32_bf16 v[28:31], v[56:59], v[28:31], 0
	ds_read_b128 v[56:59], v64 offset:2304
	ds_read_b128 v[64:67], v64 offset:2368
	s_add_i32 s20, s20, 0x1b400
	v_cmp_eq_u32_e64 s[18:19], 15, v185
	v_mfma_f32_16x16x32_bf16 v[72:75], v[52:55], v[48:51], v[32:35]
	v_lshl_add_u32 v191, v146, 2, s20
	s_nop 1
	v_lshlrev_b32_e32 v34, 2, v146
	v_add_u32_e32 v35, 0, v34
	v_mfma_f32_16x16x32_bf16 v[40:43], v[40:43], v[36:39], v[24:27]
	v_add_u32_e32 v32, 0x24900, v35
	ds_read_b128 v[84:87], v32
	s_waitcnt lgkmcnt(3)
	v_mfma_f32_16x16x32_bf16 v[24:27], v[60:63], v[36:39], v[28:31]
	v_lshlrev_b32_e32 v36, 8, v126
	s_nop 1
	v_add_u32_e32 v28, 0x24800, v35
	ds_read_b128 v[28:31], v28
	s_waitcnt lgkmcnt(3)
	v_mfma_f32_16x16x32_bf16 v[44:47], v[56:59], v[44:47], 0
	s_waitcnt lgkmcnt(0)
; __device__ __forceinline__ void phase_prep(const Params& p, unsigned char* shm) {
;     ...
;             const bf16_t* zc = zs + (tk + 1) * LZS; const bf16_t* zp = zs + tk * LZS;
; #pragma unroll
;             for (int n = 0; n < 2; ++n) {
;                 const int c4 = 32 * chh + 16 * n + 4 * fq;
;                 const f32x4 d = *(const f32x4*)(prm + c4) + accd[n], al = *(const f32x4*)(prm + 64 + c4) + acca[n];
; { const f32x2 s0 = sigmoid2((f32x2){d[0], d[1]}), s1 = sigmoid2((f32x2){d[2], d[3]}), a0 = sigmoid2((f32x2){al[0], al[1]}), a1 = sigmoid2((f32x2){al[2], al[3]});
;                   lw[n] = (f32x4){s0.x, s0.y, s1.x, s1.y} * (-0.87503886f); av[n] = (f32x4){a0.x, a0.y, a1.x, a1.y}; }
;                 { const f32x4 vc = ld_bf4(zc + 128 + c4), vp = ld_bf4(zp + 128 + c4); vm[n] = vc + *(const f32x4*)(prm + 256 + c4) * (vp - vc); }
;                 const f32x4 kc = ld_bf4(zc + 64 + c4), kpv = ld_bf4(zp + 64 + c4);
;                 const f32x4 k = kc + *(const f32x4*)(prm + 192 + c4) * (kpv - kc);
;                 kkv[n] = k * *(const f32x4*)(prm + 320 + c4);
;                 kp[n] = k * (1.0f + (av[n] - 1.0f) * *(const f32x4*)(prm + 384 + c4));
;                 const f32x4 rc = ld_bf4(zc + c4), rp = ld_bf4(zp + c4);
;                 rm[n] = rc + *(const f32x4*)(prm + 128 + c4) * (rp - rc);
;                 const f32x4 rkw = rm[n] * kp[n] * *(const f32x4*)(prm + 448 + c4);
;                 { const f32x4 sq = kkv[n] * kkv[n]; nrm += (sq[0] + sq[1]) + (sq[2] + sq[3]); }
;                 rk += rkw[0] + rkw[1] + rkw[2] + rkw[3];
; #pragma unroll
;                 for (int j = 0; j < 4; ++j) {
;                     float x = lw[n][j];
;                     x += __int_as_float(__builtin_amdgcn_update_dpp(0, __float_as_int(x), 0x111, 0xf, 0xf, false));
;                     x += __int_as_float(__builtin_amdgcn_update_dpp(0, __float_as_int(x), 0x112, 0xf, 0xf, false));
;                     x += __int_as_float(__builtin_amdgcn_update_dpp(0, __float_as_int(x), 0x114, 0xf, 0xf, false));
;                     x += __int_as_float(__builtin_amdgcn_update_dpp(0, __float_as_int(x), 0x118, 0xf, 0xf, false));
;                     cs[n][j] = x;
;                 }
;                 if (fr == 15) *(f32x4*)(tot + tt * 64 + c4) = cs[n];
	v_pk_add_f32 v[28:29], v[40:41], v[28:29]
	s_nop 0
	v_pk_mul_f32 v[28:29], v[28:29], s[4:5] op_sel_hi:[1,0]
	v_pk_add_f32 v[30:31], v[42:43], v[30:31]
	v_exp_f32_e32 v28, v28
	v_exp_f32_e32 v29, v29
	v_mfma_f32_16x16x32_bf16 v[56:59], v[64:67], v[48:51], v[44:47]
	v_mul_f32_e64 v30, v30, s4
	v_mul_f32_e64 v31, v31, s4
	v_pk_add_f32 v[28:29], v[28:29], 1.0 op_sel_hi:[1,0]
	s_nop 0
	v_rcp_f32_e32 v32, v28
	v_rcp_f32_e32 v33, v29
	v_add3_u32 v28, v143, v36, v147
	v_add_u32_e32 v28, 0xd000, v28
	v_add_u32_e32 v29, s52, v34
	v_add_u32_e32 v34, 0x24b00, v35
	ds_read2_b64 v[52:55], v28 offset0:228 offset1:244
	ds_read2_b64 v[48:51], v28 offset0:194 offset1:212
	ds_read2_b64 v[68:71], v28 offset0:162 offset1:178
	ds_read_b128 v[44:47], v29
	ds_read_b128 v[92:95], v34
	v_add_u32_e32 v29, 0x24d00, v35
	v_add_u32_e32 v34, 0x24e00, v35
	v_exp_f32_e32 v30, v30
	v_exp_f32_e32 v31, v31
	ds_read_b128 v[96:99], v29
	ds_read_b128 v[76:79], v34
	v_add_u32_e32 v29, 0x24a00, v35
	v_add_u32_e32 v34, 0x24f00, v35
	v_pk_mul_f32 v[154:155], v[32:33], s[6:7] op_sel_hi:[1,0]
	ds_read_b128 v[64:67], v29
	ds_read_b128 v[60:63], v34
	v_mov_b32_e32 v34, v127
	v_mov_b32_e32 v35, v127
	v_pk_add_f32 v[30:31], v[30:31], 1.0 op_sel_hi:[1,0]
	v_mov_b32_dpp v34, v154 row_shr:1 row_mask:0xf bank_mask:0xf
	v_mov_b32_dpp v35, v155 row_shr:1 row_mask:0xf bank_mask:0xf
	v_pk_fma_f32 v[32:33], v[32:33], s[6:7], v[34:35] op_sel_hi:[1,0,1]
	v_rcp_f32_e32 v30, v30
	v_rcp_f32_e32 v31, v31
	v_add_f32_dpp v32, v32, v32 row_shr:2 row_mask:0xf bank_mask:0xf bound_ctrl:1
	v_add_f32_dpp v33, v33, v33 row_shr:2 row_mask:0xf bank_mask:0xf bound_ctrl:1
	v_pk_mul_f32 v[152:153], v[30:31], s[6:7] op_sel_hi:[1,0]
	v_mov_b32_e32 v34, v127
	v_mov_b32_e32 v35, v127
	v_add_f32_dpp v32, v32, v32 row_shr:4 row_mask:0xf bank_mask:0xf bound_ctrl:1
	v_add_f32_dpp v33, v33, v33 row_shr:4 row_mask:0xf bank_mask:0xf bound_ctrl:1
	v_mov_b32_dpp v34, v152 row_shr:1 row_mask:0xf bank_mask:0xf
	v_mov_b32_dpp v35, v153 row_shr:1 row_mask:0xf bank_mask:0xf
	v_add_f32_dpp v40, v32, v32 row_shr:8 row_mask:0xf bank_mask:0xf bound_ctrl:1
	v_add_f32_dpp v41, v33, v33 row_shr:8 row_mask:0xf bank_mask:0xf bound_ctrl:1
	v_pk_fma_f32 v[30:31], v[30:31], s[6:7], v[34:35] op_sel_hi:[1,0,1]
	s_nop 1
	v_add_f32_dpp v30, v30, v30 row_shr:2 row_mask:0xf bank_mask:0xf bound_ctrl:1
	v_add_f32_dpp v31, v31, v31 row_shr:2 row_mask:0xf bank_mask:0xf bound_ctrl:1
	s_nop 0
	v_add_f32_dpp v30, v30, v30 row_shr:4 row_mask:0xf bank_mask:0xf bound_ctrl:1
	v_add_f32_dpp v31, v31, v31 row_shr:4 row_mask:0xf bank_mask:0xf bound_ctrl:1
	s_nop 0
	v_add_f32_dpp v42, v30, v30 row_shr:8 row_mask:0xf bank_mask:0xf bound_ctrl:1
	v_add_f32_dpp v43, v31, v31 row_shr:8 row_mask:0xf bank_mask:0xf bound_ctrl:1
	s_and_saveexec_b64 s[20:21], s[18:19]
	ds_write_b128 v191, v[40:43]
	s_or_b64 exec, exec, s[20:21]
	v_or_b32_e32 v29, 16, v146
	v_lshl_add_u32 v190, v29, 2, 0
	v_add_u32_e32 v29, 0x24800, v190
	ds_read_b128 v[30:33], v29
	v_mov_b32_e32 v196, v127
	v_mov_b32_e32 v197, v127
	v_add_u32_e32 v29, 0x24900, v190
	ds_read_b128 v[116:119], v29
	s_waitcnt lgkmcnt(1)
	v_pk_add_f32 v[24:25], v[24:25], v[30:31]
	v_pk_add_f32 v[26:27], v[26:27], v[32:33]
	v_pk_mul_f32 v[24:25], v[24:25], s[4:5] op_sel_hi:[1,0]
	v_pk_mul_f32 v[26:27], v[26:27], s[4:5] op_sel_hi:[1,0]
	v_exp_f32_e32 v24, v24
	v_exp_f32_e32 v25, v25
	v_exp_f32_e32 v26, v26
	v_exp_f32_e32 v27, v27
	v_add_u32_e32 v29, 0x24c00, v190
	v_pk_add_f32 v[24:25], v[24:25], 1.0 op_sel_hi:[1,0]
	v_add_u32_e32 v80, 0x24b00, v190
	v_rcp_f32_e32 v24, v24
	v_rcp_f32_e32 v25, v25
	v_pk_add_f32 v[26:27], v[26:27], 1.0 op_sel_hi:[1,0]
	ds_read2_b64 v[36:39], v28 offset0:232 offset1:248
	ds_read2_b64 v[32:35], v28 offset0:198 offset1:216
	v_rcp_f32_e32 v26, v26
	v_pk_mul_f32 v[150:151], v[24:25], s[6:7] op_sel_hi:[1,0]
	v_rcp_f32_e32 v27, v27
	ds_read2_b64 v[100:103], v28 offset0:166 offset1:182
	v_mov_b32_dpp v196, v150 row_shr:1 row_mask:0xf bank_mask:0xf
	v_mov_b32_dpp v197, v151 row_shr:1 row_mask:0xf bank_mask:0xf
	v_pk_fma_f32 v[24:25], v[24:25], s[6:7], v[196:197] op_sel_hi:[1,0,1]
	v_mov_b32_e32 v196, v127
	v_mov_b32_e32 v197, v127
	v_pk_mul_f32 v[148:149], v[26:27], s[6:7] op_sel_hi:[1,0]
	v_add_f32_dpp v24, v24, v24 row_shr:2 row_mask:0xf bank_mask:0xf bound_ctrl:1
	v_add_f32_dpp v25, v25, v25 row_shr:2 row_mask:0xf bank_mask:0xf bound_ctrl:1
	ds_read_b128 v[28:31], v29
	ds_read_b128 v[108:111], v80
	v_add_f32_dpp v24, v24, v24 row_shr:4 row_mask:0xf bank_mask:0xf bound_ctrl:1
	v_add_f32_dpp v25, v25, v25 row_shr:4 row_mask:0xf bank_mask:0xf bound_ctrl:1
	v_add_u32_e32 v80, 0x24d00, v190
	v_mov_b32_dpp v196, v148 row_shr:1 row_mask:0xf bank_mask:0xf
	v_mov_b32_dpp v197, v149 row_shr:1 row_mask:0xf bank_mask:0xf
	v_add_f32_dpp v24, v24, v24 row_shr:8 row_mask:0xf bank_mask:0xf bound_ctrl:1
	v_add_f32_dpp v25, v25, v25 row_shr:8 row_mask:0xf bank_mask:0xf bound_ctrl:1
	v_add_u32_e32 v81, 0x24e00, v190
	v_pk_fma_f32 v[26:27], v[26:27], s[6:7], v[196:197] op_sel_hi:[1,0,1]
	ds_read_b128 v[112:115], v80
	ds_read_b128 v[104:107], v81
	v_add_u32_e32 v80, 0x24a00, v190
	v_add_u32_e32 v81, 0x24f00, v190
	v_add_f32_dpp v26, v26, v26 row_shr:2 row_mask:0xf bank_mask:0xf bound_ctrl:1
	v_add_f32_dpp v27, v27, v27 row_shr:2 row_mask:0xf bank_mask:0xf bound_ctrl:1
	ds_read_b128 v[88:91], v80
	ds_read_b128 v[80:83], v81
	v_add_f32_dpp v26, v26, v26 row_shr:4 row_mask:0xf bank_mask:0xf bound_ctrl:1
	v_add_f32_dpp v27, v27, v27 row_shr:4 row_mask:0xf bank_mask:0xf bound_ctrl:1
	s_nop 0
	v_add_f32_dpp v26, v26, v26 row_shr:8 row_mask:0xf bank_mask:0xf bound_ctrl:1
	v_add_f32_dpp v27, v27, v27 row_shr:8 row_mask:0xf bank_mask:0xf bound_ctrl:1
; __device__ __forceinline__ f32x4 ld_bf4(const bf16_t* p) { const u32x2 u = *(const u32x2*)p; return (f32x4){bf_lo(u.x), bf_hi(u.x), bf_lo(u.y), bf_hi(u.y)}; }
; __device__ __forceinline__ void phase_prep(const Params& p, unsigned char* shm) {
;     ...
; { const f32x2 s0 = sigmoid2((f32x2){d[0], d[1]}), s1 = sigmoid2((f32x2){d[2], d[3]}), a0 = sigmoid2((f32x2){al[0], al[1]}), a1 = sigmoid2((f32x2){al[2], al[3]});
;                   lw[n] = (f32x4){s0.x, s0.y, s1.x, s1.y} * (-0.87503886f); av[n] = (f32x4){a0.x, a0.y, a1.x, a1.y}; }
;                 { const f32x4 vc = ld_bf4(zc + 128 + c4), vp = ld_bf4(zp + 128 + c4); vm[n] = vc + *(const f32x4*)(prm + 256 + c4) * (vp - vc); }
;                 const f32x4 kc = ld_bf4(zc + 64 + c4), kpv = ld_bf4(zp + 64 + c4);
;                 const f32x4 k = kc + *(const f32x4*)(prm + 192 + c4) * (kpv - kc);
;                 kkv[n] = k * *(const f32x4*)(prm + 320 + c4);
;                 kp[n] = k * (1.0f + (av[n] - 1.0f) * *(const f32x4*)(prm + 384 + c4));
;                 const f32x4 rc = ld_bf4(zc + c4), rp = ld_bf4(zp + c4);
;                 rm[n] = rc + *(const f32x4*)(prm + 128 + c4) * (rp - rc);
;                 const f32x4 rkw = rm[n] * kp[n] * *(const f32x4*)(prm + 448 + c4);
;                 { const f32x4 sq = kkv[n] * kkv[n]; nrm += (sq[0] + sq[1]) + (sq[2] + sq[3]); }
;                 rk += rkw[0] + rkw[1] + rkw[2] + rkw[3];
; #pragma unroll
;                 for (int j = 0; j < 4; ++j) {
;                     float x = lw[n][j];
;                     x += __int_as_float(__builtin_amdgcn_update_dpp(0, __float_as_int(x), 0x111, 0xf, 0xf, false));
;                     x += __int_as_float(__builtin_amdgcn_update_dpp(0, __float_as_int(x), 0x112, 0xf, 0xf, false));
;                     x += __int_as_float(__builtin_amdgcn_update_dpp(0, __float_as_int(x), 0x114, 0xf, 0xf, false));
;                     x += __int_as_float(__builtin_amdgcn_update_dpp(0, __float_as_int(x), 0x118, 0xf, 0xf, false));
;                     cs[n][j] = x;
;                 }
;                 if (fr == 15) *(f32x4*)(tot + tt * 64 + c4) = cs[n];
;             }
;             nrm += __shfl_xor(nrm, 16); nrm += __shfl_xor(nrm, 32);
;             rk += __shfl_xor(rk, 16); rk += __shfl_xor(rk, 32);
;             if (fq == 0) { red[wid * 16 + fr] = nrm; red[128 + wid * 16 + fr] = rk; }
;         }
;         LDS_BARRIER();
	s_and_saveexec_b64 s[20:21], s[18:19]
	ds_write_b128 v191, v[24:27] offset:64
	s_or_b64 exec, exec, s[20:21]
	v_pk_add_f32 v[74:75], v[74:75], v[86:87]
	v_pk_add_f32 v[72:73], v[72:73], v[84:85]
	v_pk_mul_f32 v[74:75], v[74:75], s[4:5] op_sel_hi:[1,0]
	v_pk_mul_f32 v[72:73], v[72:73], s[4:5] op_sel_hi:[1,0]
	v_exp_f32_e32 v74, v74
	v_exp_f32_e32 v75, v75
	v_exp_f32_e32 v72, v72
	v_exp_f32_e32 v73, v73
	v_lshlrev_b32_e32 v84, 16, v52
	v_pk_add_f32 v[74:75], v[74:75], 1.0 op_sel_hi:[1,0]
	v_and_b32_e32 v85, 0xffff0000, v52
	v_pk_add_f32 v[72:73], v[72:73], 1.0 op_sel_hi:[1,0]
	v_rcp_f32_e32 v74, v74
	v_rcp_f32_e32 v75, v75
	v_rcp_f32_e32 v72, v72
	v_rcp_f32_e32 v73, v73
	v_lshlrev_b32_e32 v52, 16, v53
	v_and_b32_e32 v53, 0xffff0000, v53
	v_lshlrev_b32_e32 v86, 16, v70
	v_and_b32_e32 v87, 0xffff0000, v70
	v_lshlrev_b32_e32 v70, 16, v71
	v_and_b32_e32 v71, 0xffff0000, v71
	v_sub_f32_e32 v71, v71, v53
	v_sub_f32_e32 v70, v70, v52
	v_pk_fma_f32 v[52:53], v[94:95], v[70:71], v[52:53]
	v_pk_add_f32 v[94:95], v[74:75], -1.0 op_sel_hi:[1,0]
	v_sub_f32_e32 v87, v87, v85
	v_sub_f32_e32 v86, v86, v84
	v_pk_add_f32 v[70:71], v[72:73], -1.0 op_sel_hi:[1,0]
	v_pk_fma_f32 v[78:79], v[78:79], v[94:95], 1.0 op_sel_hi:[1,1,0]
	v_pk_fma_f32 v[92:93], v[92:93], v[86:87], v[84:85]
	v_pk_mul_f32 v[84:85], v[98:99], v[52:53]
	v_pk_fma_f32 v[70:71], v[76:77], v[70:71], 1.0 op_sel_hi:[1,1,0]
	v_pk_mul_f32 v[76:77], v[52:53], v[78:79]
	v_lshlrev_b32_e32 v52, 16, v50
	v_and_b32_e32 v53, 0xffff0000, v50
	v_lshlrev_b32_e32 v78, 16, v68
	v_and_b32_e32 v68, 0xffff0000, v68
	v_pk_mul_f32 v[86:87], v[96:97], v[92:93]
	v_pk_mul_f32 v[70:71], v[92:93], v[70:71]
	v_lshlrev_b32_e32 v50, 16, v51
	v_and_b32_e32 v51, 0xffff0000, v51
	v_lshlrev_b32_e32 v92, 16, v69
	v_and_b32_e32 v79, 0xffff0000, v69
	v_sub_f32_e32 v69, v68, v53
	v_sub_f32_e32 v68, v78, v52
	v_sub_f32_e32 v79, v79, v51
	v_sub_f32_e32 v78, v92, v50
	v_pk_fma_f32 v[64:65], v[64:65], v[68:69], v[52:53]
	v_pk_fma_f32 v[66:67], v[66:67], v[78:79], v[50:51]
	v_pk_mul_f32 v[50:51], v[70:71], v[64:65]
	v_pk_mul_f32 v[52:53], v[76:77], v[66:67]
	v_pk_mul_f32 v[50:51], v[60:61], v[50:51]
	v_pk_mul_f32 v[52:53], v[62:63], v[52:53]
	v_add_f32_e32 v50, v50, v51
	v_add_f32_e32 v50, v52, v50
	v_add_f32_e32 v50, v53, v50
	v_add_f32_e32 v93, 0, v50
	s_waitcnt lgkmcnt(9)
	v_pk_add_f32 v[50:51], v[58:59], v[118:119]
	v_pk_add_f32 v[52:53], v[56:57], v[116:117]
	v_pk_mul_f32 v[50:51], v[50:51], s[4:5] op_sel_hi:[1,0]
	v_pk_mul_f32 v[52:53], v[52:53], s[4:5] op_sel_hi:[1,0]
	v_exp_f32_e32 v56, v50
	v_exp_f32_e32 v52, v52
	v_exp_f32_e32 v53, v53
	v_exp_f32_e32 v57, v51
	v_pk_mul_f32 v[60:61], v[84:85], v[84:85]
	v_pk_mul_f32 v[62:63], v[86:87], v[86:87]
	v_pk_add_f32 v[50:51], v[52:53], 1.0 op_sel_hi:[1,0]
	v_pk_add_f32 v[52:53], v[56:57], 1.0 op_sel_hi:[1,0]
	v_rcp_f32_e32 v50, v50
	v_rcp_f32_e32 v51, v51
	v_rcp_f32_e32 v52, v52
	v_rcp_f32_e32 v53, v53
	v_add_f32_e32 v62, v62, v63
	v_add_f32_e32 v60, v60, v61
	s_waitcnt lgkmcnt(8)
	v_lshlrev_b32_e32 v56, 16, v36
	v_and_b32_e32 v57, 0xffff0000, v36
	v_lshlrev_b32_e32 v36, 16, v37
	v_and_b32_e32 v37, 0xffff0000, v37
	s_waitcnt lgkmcnt(6)
	v_lshlrev_b32_e32 v58, 16, v103
	v_and_b32_e32 v59, 0xffff0000, v103
	v_add_f32_e32 v92, v62, v60
	v_lshlrev_b32_e32 v60, 16, v102
	v_and_b32_e32 v61, 0xffff0000, v102
	v_sub_f32_e32 v59, v59, v37
	v_sub_f32_e32 v58, v58, v36
	v_sub_f32_e32 v61, v61, v57
	v_sub_f32_e32 v60, v60, v56
	s_waitcnt lgkmcnt(4)
	v_pk_fma_f32 v[62:63], v[110:111], v[58:59], v[36:37]
	v_pk_add_f32 v[36:37], v[50:51], -1.0 op_sel_hi:[1,0]
	v_pk_add_f32 v[68:69], v[52:53], -1.0 op_sel_hi:[1,0]
	v_pk_fma_f32 v[56:57], v[108:109], v[60:61], v[56:57]
	s_waitcnt lgkmcnt(2)
	v_pk_fma_f32 v[68:69], v[106:107], v[68:69], 1.0 op_sel_hi:[1,1,0]
	v_pk_fma_f32 v[36:37], v[104:105], v[36:37], 1.0 op_sel_hi:[1,1,0]
	v_pk_mul_f32 v[58:59], v[114:115], v[62:63]
	v_pk_mul_f32 v[60:61], v[112:113], v[56:57]
	v_pk_mul_f32 v[36:37], v[56:57], v[36:37]
	v_pk_mul_f32 v[56:57], v[62:63], v[68:69]
	v_lshlrev_b32_e32 v62, 16, v34
	v_and_b32_e32 v63, 0xffff0000, v34
	v_lshlrev_b32_e32 v34, 16, v35
	v_and_b32_e32 v35, 0xffff0000, v35
	v_lshlrev_b32_e32 v68, 16, v100
	v_and_b32_e32 v69, 0xffff0000, v100
	v_lshlrev_b32_e32 v78, 16, v101
	v_and_b32_e32 v79, 0xffff0000, v101
	v_sub_f32_e32 v69, v69, v63
	v_sub_f32_e32 v68, v68, v62
	v_sub_f32_e32 v79, v79, v35
	v_sub_f32_e32 v78, v78, v34
	s_waitcnt lgkmcnt(1)
	v_pk_fma_f32 v[34:35], v[90:91], v[78:79], v[34:35]
	v_pk_fma_f32 v[62:63], v[88:89], v[68:69], v[62:63]
	v_pk_mul_f32 v[78:79], v[56:57], v[34:35]
	v_pk_mul_f32 v[68:69], v[36:37], v[62:63]
	s_waitcnt lgkmcnt(0)
	v_pk_mul_f32 v[78:79], v[82:83], v[78:79]
	v_pk_mul_f32 v[68:69], v[80:81], v[68:69]
	v_pk_mul_f32 v[80:81], v[58:59], v[58:59]
	v_pk_mul_f32 v[82:83], v[60:61], v[60:61]
	v_add_f32_e32 v80, v80, v81
	v_add_f32_e32 v82, v82, v83
	v_add_f32_e32 v80, v82, v80
	v_and_b32_e32 v82, 64, v180
	v_xor_b32_e32 v81, 16, v180
	v_add_u32_e32 v82, 64, v82
	v_add_f32_e32 v68, v68, v69
	v_cmp_lt_i32_e32 vcc, v81, v82
	v_add_f32_e32 v68, v78, v68
	v_add_f32_e32 v68, v79, v68
	v_cndmask_b32_e32 v81, v180, v81, vcc
	v_add_f32_e32 v80, v92, v80
	v_lshlrev_b32_e32 v81, 2, v81
	v_add_f32_e32 v68, v93, v68
	ds_bpermute_b32 v83, v81, v80
	ds_bpermute_b32 v79, v81, v68
	v_xor_b32_e32 v78, 32, v180
	v_cmp_lt_i32_e32 vcc, v78, v82
	s_ashr_i32 s71, s25, 6
	s_waitcnt lgkmcnt(1)
	v_add_f32_e32 v69, v80, v83
	v_cndmask_b32_e32 v78, v180, v78, vcc
	v_lshlrev_b32_e32 v78, 2, v78
	s_waitcnt lgkmcnt(0)
	v_add_f32_e32 v79, v68, v79
	ds_bpermute_b32 v80, v78, v69
	ds_bpermute_b32 v81, v78, v79
	v_and_b32_e32 v68, 63, v187
	s_ashr_i32 s27, s26, 31
	v_cmp_gt_u32_e32 vcc, 16, v68
	s_waitcnt lgkmcnt(1)
	v_add_f32_e32 v78, v69, v80
	s_waitcnt lgkmcnt(0)
	v_add_f32_e32 v69, v79, v81
	s_lshl_b32 s72, s71, 4
	s_and_saveexec_b64 s[20:21], vcc
	s_lshl_b32 s23, s72, 2
	s_add_i32 s23, s23, 0
	v_lshl_add_u32 v79, v185, 2, s23
	v_add_u32_e32 v79, 0x1b000, v79
	ds_write2st64_b32 v79, v78, v69 offset1:2
	s_or_b64 exec, exec, s[20:21]
	s_xor_b32 s20, s72, 64
	s_lshl_b32 s20, s20, 2
	s_add_i32 s20, s20, 0
	v_lshl_add_u32 v81, v185, 2, s20
	s_waitcnt lgkmcnt(0)
	s_barrier
; __device__ __forceinline__ void st_bf4(bf16_t* p, f32x4 v) { u32x2 u; u.x = pk_bf16(v[0], v[1]); u.y = pk_bf16(v[2], v[3]); *(u32x2*)p = u; }
; __device__ __forceinline__ void phase_prep(const Params& p, unsigned char* shm) {
;     ...
;         {
;             nrm += red[(wid ^ 4) * 16 + fr]; rk += red[128 + (wid ^ 4) * 16 + fr];
;             const float inv = 1.0f / fmaxf(sqrtf(nrm), 1e-12f);
;             p.PRK[(size_t)row * 16 + h] = rk;
; #pragma unroll
;             for (int n = 0; n < 2; ++n) {
;                 const int c4 = 32 * chh + 16 * n + 4 * fq;
;                 f32x4 pre = (f32x4){0.f, 0.f, 0.f, 0.f}, total = (f32x4){0.f, 0.f, 0.f, 0.f};
; #pragma unroll
;                 for (int t2 = 0; t2 < 4; ++t2) { const f32x4 x = *(const f32x4*)(tot + t2 * 64 + c4); total += x; if (t2 < tt) pre += x; }
;                 const f32x4 csum = pre + cs[n];
;                 f32x4 eg, eng, egm, etc; const f32x4 ncs = -csum, cml = csum - lw[n], tmc = total - csum;
; #pragma unroll
;                 for (int j = 0; j < 4; ++j) { eg[j] = __builtin_amdgcn_exp2f(csum[j]); eng[j] = __builtin_amdgcn_exp2f(ncs[j]); egm[j] = __builtin_amdgcn_exp2f(cml[j]); etc[j] = __builtin_amdgcn_exp2f(tmc[j]); }
;                 const f32x4 kkn = kkv[n] * inv, bb = kkn * av[n];
;                 const f32x4 qt = rm[n] * eg, kt = kp[n] * eng, bt = bb * eng, kkt = kkn * egm, kpp = kp[n] * etc, bpp = bb * etc;
;                 st_bf4(Qt + tk * LD + c4, qt); st_bf4(Kt + tk * LD + c4, kt); st_bf4(Bt + tk * LD + c4, bt);
;                 const u32x2 kkw = pk_bf4(kkt), vmw = pk_bf4(vm[n]), kpw = pk_bf4(kpp), bpw = pk_bf4(bpp);
;                 *(u32x2*)(KKt + tk * LD + c4) = kkw;
;                 { bf16_t* d = KKtT + c4 * LD + tk; d[0] = (bf16_t)kkw.x; d[LD] = (bf16_t)(kkw.x >> 16); d[2 * LD] = (bf16_t)kkw.y; d[3 * LD] = (bf16_t)(kkw.y >> 16); }
;                 { bf16_t* d = VmT + c4 * LD + tk; d[0] = (bf16_t)vmw.x; d[LD] = (bf16_t)(vmw.x >> 16); d[2 * LD] = (bf16_t)vmw.y; d[3 * LD] = (bf16_t)(vmw.y >> 16); }
;                 { bf16_t* d = KpT + c4 * LD + tk; d[0] = (bf16_t)kpw.x; d[LD] = (bf16_t)(kpw.x >> 16); d[2 * LD] = (bf16_t)kpw.y; d[3 * LD] = (bf16_t)(kpw.y >> 16); }
;                 { bf16_t* d = BpT + c4 * LD + tk; d[0] = (bf16_t)bpw.x; d[LD] = (bf16_t)(bpw.x >> 16); d[2 * LD] = (bf16_t)bpw.y; d[3 * LD] = (bf16_t)(bpw.y >> 16); }
	v_add_u32_e32 v81, 0x1b000, v81
	ds_read2st64_b32 v[88:89], v81 offset1:2
	v_and_b32_e32 v83, 0xffff0000, v54
	v_lshlrev_b32_e32 v79, 16, v48
	v_and_b32_e32 v48, 0xffff0000, v48
	v_lshlrev_b32_e32 v81, 16, v49
	v_and_b32_e32 v90, 0xffff0000, v49
	v_sub_f32_e32 v49, v48, v83
	s_waitcnt lgkmcnt(0)
	v_add_f32_e32 v48, v78, v88
	v_mul_f32_e32 v78, 0x4f800000, v48
	v_cmp_gt_f32_e32 vcc, s53, v48
	v_lshlrev_b32_e32 v82, 16, v54
	v_lshlrev_b32_e32 v54, 16, v55
	v_cndmask_b32_e32 v88, v48, v78, vcc
	v_sqrt_f32_e32 v91, v88
	v_and_b32_e32 v55, 0xffff0000, v55
	v_sub_f32_e32 v78, v81, v54
	v_sub_f32_e32 v48, v79, v82
	v_add_u32_e32 v81, -1, v91
	v_sub_f32_e32 v79, v90, v55
	v_fma_f32 v90, -v81, v91, v88
	v_cmp_ge_f32_e64 s[20:21], 0, v90
	v_add_u32_e32 v90, 1, v91
	v_pk_fma_f32 v[82:83], v[44:45], v[48:49], v[82:83]
	v_cndmask_b32_e64 v81, v91, v81, s[20:21]
	v_fma_f32 v91, -v90, v91, v88
	v_cmp_lt_f32_e64 s[20:21], 0, v91
	v_pk_fma_f32 v[54:55], v[46:47], v[78:79], v[54:55]
	v_or_b32_e32 v80, s24, v126
	v_cndmask_b32_e64 v81, v81, v90, s[20:21]
	v_mul_f32_e32 v90, 0x37800000, v81
	v_cndmask_b32_e32 v81, v81, v90, vcc
	v_cmp_class_f32_e32 vcc, v88, v181
	s_lshl_b32 s40, s22, 2
	v_add_f32_e32 v45, v69, v89
	v_cndmask_b32_e32 v81, v81, v88, vcc
	v_max_f32_e32 v81, 0x2b8cbccc, v81
	v_div_scale_f32 v88, s[20:21], v81, v81, 1.0
	v_rcp_f32_e32 v90, v88
	s_mov_b64 s[20:21], s[92:93]
	s_cmp_eq_u32 s28, 0
	s_cselect_b64 s[24:25], -1, 0
	v_fma_f32 v44, -v88, v90, 1.0
	v_fmac_f32_e32 v90, v44, v90
	v_div_scale_f32 v44, vcc, 1.0, v81, 1.0
	v_mul_f32_e32 v46, v44, v90
	v_fma_f32 v47, -v88, v46, v44
	v_fmac_f32_e32 v46, v47, v90
	v_fma_f32 v44, -v88, v46, v44
	v_div_fmas_f32 v44, v44, v90, v46
	v_div_fixup_f32 v44, v44, v81, 1.0
	v_ashrrev_i32_e32 v81, 31, v80
	v_lshlrev_b64 v[46:47], 6, v[80:81]
	s_waitcnt lgkmcnt(0)
	v_lshl_add_u64 v[46:47], s[20:21], 0, v[46:47]
	v_lshl_add_u64 v[46:47], v[46:47], 0, s[40:41]
	global_store_dword v[46:47], v45, off
	v_lshl_add_u32 v46, v146, 2, 0
	v_add_u32_e32 v69, 0x1b400, v46
	ds_read_b128 v[46:49], v69
	ds_read_b128 v[78:81], v69 offset:256
	s_lshl_b64 s[22:23], s[26:27], 8
	s_cmp_gt_u32 s28, 1
	ds_read_b128 v[88:91], v69 offset:512
	s_waitcnt lgkmcnt(2)
	v_pk_add_f32 v[48:49], v[48:49], 0 op_sel_hi:[1,0]
	s_cselect_b64 vcc, -1, 0
	v_cndmask_b32_e64 v93, v49, 0, s[24:25]
	v_cndmask_b32_e64 v92, v48, 0, s[24:25]
	s_waitcnt lgkmcnt(1)
	v_pk_add_f32 v[94:95], v[80:81], v[92:93]
	v_pk_add_f32 v[46:47], v[46:47], 0 op_sel_hi:[1,0]
	v_cndmask_b32_e32 v97, v93, v95, vcc
	v_cndmask_b32_e32 v96, v92, v94, vcc
	ds_read_b128 v[92:95], v69 offset:768
	v_cndmask_b32_e64 v101, v47, 0, s[24:25]
	v_cndmask_b32_e64 v100, v46, 0, s[24:25]
	v_pk_add_f32 v[46:47], v[46:47], v[78:79]
	v_pk_add_f32 v[78:79], v[78:79], v[100:101]
	s_cmp_eq_u32 s28, 3
	v_cndmask_b32_e32 v79, v101, v79, vcc
	v_cndmask_b32_e32 v78, v100, v78, vcc
	s_waitcnt lgkmcnt(1)
	v_pk_add_f32 v[98:99], v[90:91], v[96:97]
	s_cselect_b64 s[20:21], -1, 0
	v_pk_add_f32 v[48:49], v[48:49], v[80:81]
	v_pk_add_f32 v[80:81], v[46:47], v[88:89]
	v_pk_add_f32 v[46:47], v[88:89], v[78:79]
	v_pk_add_f32 v[48:49], v[48:49], v[90:91]
	v_cndmask_b32_e64 v89, v97, v99, s[20:21]
	v_cndmask_b32_e64 v88, v96, v98, s[20:21]
	v_cndmask_b32_e64 v79, v79, v47, s[20:21]
	v_cndmask_b32_e64 v78, v78, v46, s[20:21]
	s_waitcnt lgkmcnt(0)
	v_pk_add_f32 v[46:47], v[48:49], v[94:95]
	v_pk_add_f32 v[48:49], v[80:81], v[92:93]
	v_pk_add_f32 v[42:43], v[42:43], v[88:89]
	v_pk_add_f32 v[40:41], v[40:41], v[78:79]
	v_sub_f32_e32 v91, v46, v42
	v_sub_f32_e32 v79, v48, v40
	v_sub_f32_e32 v69, v47, v43
	v_sub_f32_e32 v89, v49, v41
	v_exp_f32_e32 v78, v40
	v_exp_f32_e64 v80, -v40
	v_sub_f32_e32 v40, v40, v154
	v_exp_f32_e32 v88, v79
	v_exp_f32_e32 v79, v41
	v_exp_f32_e64 v81, -v41
	v_sub_f32_e32 v41, v41, v155
	v_exp_f32_e32 v90, v42
	v_exp_f32_e64 v92, -v42
	v_sub_f32_e32 v42, v42, v152
	v_exp_f32_e32 v94, v91
	v_exp_f32_e32 v91, v43
	v_exp_f32_e64 v93, -v43
	v_sub_f32_e32 v43, v43, v153
	v_mul_u32_u24_e32 v45, 0x48, v126
	v_exp_f32_e32 v40, v40
	v_exp_f32_e32 v41, v41
	v_exp_f32_e32 v42, v42
	v_exp_f32_e32 v43, v43
	v_lshlrev_b32_e32 v45, 1, v45
	v_pk_mul_f32 v[84:85], v[84:85], v[44:45] op_sel_hi:[1,0]
	v_pk_mul_f32 v[86:87], v[86:87], v[44:45] op_sel_hi:[1,0]
	v_exp_f32_e32 v89, v89
	v_pk_mul_f32 v[72:73], v[72:73], v[86:87]
	v_pk_mul_f32 v[74:75], v[74:75], v[84:85]
	v_pk_mul_f32 v[66:67], v[66:67], v[90:91]
	v_pk_mul_f32 v[64:65], v[64:65], v[78:79]
	v_pk_mul_f32 v[78:79], v[76:77], v[92:93]
	v_pk_mul_f32 v[90:91], v[70:71], v[80:81]
	v_exp_f32_e32 v95, v69
	v_pk_mul_f32 v[92:93], v[74:75], v[92:93]
	v_pk_mul_f32 v[80:81], v[72:73], v[80:81]
	v_pk_mul_f32 v[42:43], v[84:85], v[42:43]
	v_pk_mul_f32 v[84:85], v[86:87], v[40:41]
	v_add3_u32 v40, 0, v45, v147
	v_cvt_pk_bf16_f32 v64, v64, v65
	v_cvt_pk_bf16_f32 v65, v66, v67
	v_cvt_pk_bf16_f32 v66, v90, v91
	v_cvt_pk_bf16_f32 v67, v78, v79
	ds_write2st64_b64 v40, v[64:65], v[66:67] offset0:72 offset1:90
	v_cvt_pk_bf16_f32 v64, v80, v81
	v_cvt_pk_bf16_f32 v65, v92, v93
	v_cvt_pk_bf16_f32 v66, v84, v85
	v_cvt_pk_bf16_f32 v67, v42, v43
	v_lshlrev_b32_e32 v102, 1, v126
	ds_write2st64_b64 v40, v[64:65], v[66:67] offset0:108 offset1:126
	v_mul_u32_u24_e32 v64, s50, v146
	v_pk_mul_f32 v[70:71], v[70:71], v[88:89]
	v_pk_mul_f32 v[72:73], v[72:73], v[88:89]
	v_cvt_pk_bf16_f32 v41, v82, v83
	v_add3_u32 v42, s55, v102, v64
	v_add3_u32 v43, s56, v102, v64
	s_cmp_lg_u32 s28, 0
	v_pk_mul_f32 v[76:77], v[76:77], v[94:95]
	v_pk_mul_f32 v[74:75], v[74:75], v[94:95]
	v_cvt_pk_bf16_f32 v45, v54, v55
	v_cvt_pk_bf16_f32 v55, v70, v71
	v_cvt_pk_bf16_f32 v70, v72, v73
	ds_write_b16 v42, v66
	ds_write_b16_d16_hi v42, v66 offset:144
	ds_write_b16 v42, v67 offset:288
	ds_write_b16_d16_hi v42, v67 offset:432
	ds_write_b16 v43, v41
	ds_write_b16_d16_hi v43, v41 offset:144
	ds_write_b16 v43, v45 offset:288
	ds_write_b16_d16_hi v43, v45 offset:432
	v_add3_u32 v54, s57, v102, v64
	v_add3_u32 v41, s58, v102, v64
	v_cvt_pk_bf16_f32 v69, v76, v77
	v_cvt_pk_bf16_f32 v71, v74, v75
	ds_write_b16 v54, v55
	ds_write_b16_d16_hi v54, v55 offset:144
	ds_write_b16 v54, v69 offset:288
	ds_write_b16_d16_hi v54, v69 offset:432
	ds_write_b16 v41, v70
	ds_write_b16_d16_hi v41, v70 offset:144
	ds_write_b16 v41, v71 offset:288
	ds_write_b16_d16_hi v41, v71 offset:432
	s_cbranch_scc1 .LBB0_197
	s_mov_b64 s[30:31], s[94:95]
	v_exp_f32_e32 v64, v48
	v_exp_f32_e32 v65, v49
	v_exp_f32_e32 v66, v46
	v_exp_f32_e32 v67, v47
	s_waitcnt lgkmcnt(0)
	s_add_u32 s30, s30, s22
	v_ashrrev_i32_e32 v147, 31, v146
	s_addc_u32 s31, s31, s23
	v_lshl_add_u64 v[46:47], v[146:147], 2, s[30:31]
	global_store_dwordx4 v[46:47], v[64:67], off

; #define MFMA16(a, b, c) __builtin_amdgcn_mfma_f32_16x16x32_bf16(a, b, c, 0, 0, 0)
; __device__ __forceinline__ void phase_prep(const Params& p, unsigned char* shm) {
;     ...
;         {
;             const int nt = wid & 3; const bf16x8 b0 = ldfrag(KKt, LD, 16 * nt, 0, fr, fq), b1 = ldfrag(KKt, LD, 16 * nt, 32, fr, fq);
; #pragma unroll
;             for (int q = 0; q < 2; ++q) {
;                 const int ms = 2 * (wid >> 2) + q; f32x4 c1 = (f32x4){0.f, 0.f, 0.f, 0.f};
;                 if (ms <= nt) {
;                     c1 = MFMA16(ldfrag(Bt, LD, 16 * ms, 0, fr, fq), b0, c1); c1 = MFMA16(ldfrag(Bt, LD, 16 * ms, 32, fr, fq), b1, c1);
;                     if (ms == nt) {
; #pragma unroll
;                         for (int j = 0; j < 4; ++j) if (4 * fq + j >= fr) c1[j] = 0.f;
;                     }
;                 }
;                 *(f32x4*)(Aab + (16 * nt + fr) * 68 + 16 * ms + 4 * fq) = c1;
;             }
.LBB0_202:
	v_lshlrev_b32_e32 v25, 7, v126
	v_add3_u32 v42, v143, v25, v141
	v_lshl_add_u32 v25, s29, 7, v42
	s_or_b32 s29, s30, 1
	s_nop 2
	ds_write_b128 v25, v[36:39]
	s_cmp_ge_i32 s30, s28
	v_mov_b32_e32 v25, 0
	v_mov_b32_e32 v26, 0
	v_mov_b32_e32 v27, 0
	s_cbranch_scc1 .LBB0_205
	v_lshl_or_b32 v24, s29, 4, v185
	v_mul_u32_u24_e32 v24, s50, v24
	v_add3_u32 v36, 0, v24, v40
	ds_read_b128 v[24:27], v36 offset:55296
	ds_read_b128 v[36:39], v36 offset:55360
	s_cmp_lg_u32 s29, s28
	s_waitcnt lgkmcnt(1)
	v_mfma_f32_16x16x32_bf16 v[24:27], v[24:27], v[32:35], 0
	s_waitcnt lgkmcnt(0)
	v_mfma_f32_16x16x32_bf16 v[24:27], v[36:39], v[28:31], v[24:27]
	s_cbranch_scc1 .LBB0_205
	v_or_b32_e32 v28, 1, v139
	v_cmp_lt_u32_e64 s[20:21], v28, v185
	v_or_b32_e32 v28, 2, v139
	v_cmp_lt_u32_e64 s[22:23], v28, v185
	v_or_b32_e32 v28, 3, v139
	v_cmp_lt_u32_e64 s[24:25], v28, v185
	s_or_b64 s[22:23], s[24:25], s[22:23]
	v_cmp_lt_u32_e32 vcc, v139, v185
	s_or_b64 s[20:21], s[22:23], s[20:21]
	s_or_b64 vcc, s[20:21], vcc
	v_cndmask_b32_e64 v27, 0, v27, s[24:25]
	v_cndmask_b32_e64 v26, 0, v26, s[22:23]
	v_cndmask_b32_e64 v25, 0, v25, s[20:21]
	v_cndmask_b32_e32 v24, 0, v24, vcc

; __device__ __forceinline__ void st_bf4(bf16_t* p, f32x4 v) { u32x2 u; u.x = pk_bf16(v[0], v[1]); u.y = pk_bf16(v[2], v[3]); *(u32x2*)p = u; }
; #define MFMA16(a, b, c) __builtin_amdgcn_mfma_f32_16x16x32_bf16(a, b, c, 0, 0, 0)
; __device__ __forceinline__ void phase_prep(const Params& p, unsigned char* shm) {
;     ...
;         {
;             *(u32x4*)(p.VKG + chbase + crow * 64 + cseg) = *(const u32x4*)(VKt + crow * LD + cseg);
;             *(u32x4*)(p.YVG + chbase + crow * 64 + cseg) = *(const u32x4*)(YVt + crow * LD + cseg);
; #pragma unroll
;             for (int i = 0; i < 4; ++i) {
;                 const int idx = wid + 8 * i; f32x4 c = (f32x4){0.f, 0.f, 0.f, 0.f};
;                 if (idx < 16) { const int mk = idx >> 2, nt = idx & 3;
;                     c = MFMA16(ldfrag(KKtT, LD, 16 * mk, 0, fr, fq), ldfrag(Tm, LD, 16 * nt, 0, fr, fq), c);
;                     c = MFMA16(ldfrag(KKtT, LD, 16 * mk, 32, fr, fq), ldfrag(Tm, LD, 16 * nt, 32, fr, fq), c);
;                     st_bf4(W1t + (16 * nt + fr) * LD + 16 * mk + 4 * fq, -c);
;                 } else { const int i2 = idx - 16, mt = i2 >> 2, nv = i2 & 3;
;                     c = MFMA16(ldfrag(Tm, LD, 16 * mt, 0, fr, fq), ldfrag(XT, LD, 16 * nv, 0, fr, fq), c);
;                     c = MFMA16(ldfrag(Tm, LD, 16 * mt, 32, fr, fq), ldfrag(XT, LD, 16 * nv, 32, fr, fq), c);
;                     st_bf4(U0t + (16 * nv + fr) * LD + 16 * mt + 4 * fq, -c);
;                 }
;             }
.LBB0_256:
	s_mov_b64 s[20:21], s[98:99]
	s_mov_b64 s[22:23], s[100:101]
	v_mul_u32_u24_e32 v24, s54, v186
	v_lshlrev_b32_e32 v26, 1, v24
	v_add3_u32 v24, 0, v26, v144
	ds_read_b128 v[28:31], v24 offset:26624
	s_lshl_b64 s[18:19], s[44:45], 1
	v_lshlrev_b32_e32 v24, 6, v186
	s_waitcnt lgkmcnt(0)
	s_add_u32 s22, s22, s18
	v_ashrrev_i32_e32 v25, 31, v24
	s_addc_u32 s23, s23, s19
	v_lshlrev_b64 v[24:25], 1, v[24:25]
	v_lshl_add_u64 v[32:33], s[22:23], 0, v[24:25]
	v_mov_b32_e32 v145, v127
	v_add3_u32 v27, s57, v26, v144
	v_lshl_add_u64 v[36:37], v[32:33], 0, v[144:145]
	ds_read_b128 v[32:35], v27
	s_add_u32 s20, s20, s18
	s_addc_u32 s21, s21, s19
	global_store_dwordx4 v[36:37], v[28:31], off
	v_and_or_b32 v27, s72, 48, v185
	s_lshl_b32 s22, s71, 2
	v_lshl_add_u64 v[28:29], s[20:21], 0, v[24:25]
	v_lshl_add_u64 v[28:29], v[28:29], 0, v[144:145]
	s_waitcnt lgkmcnt(0)
	global_store_dwordx4 v[28:29], v[32:35], off
	v_mul_u32_u24_e32 v29, 0x90, v27
	v_add3_u32 v27, 0, v29, v40
	v_add3_u32 v28, s56, v29, v41
	s_cmp_gt_i32 s71, 15
	s_mov_b64 s[20:21], -1
	s_cbranch_scc0 .LBB0_264
	s_and_b32 s20, s22, 0x7ffffff0
	s_sub_i32 s20, s20, 64
	v_or_b32_e32 v30, s20, v185
	v_mul_u32_u24_e32 v30, s50, v30
	v_add3_u32 v34, 0, v30, v40
	ds_read_b128 v[30:33], v34 offset:17408
	ds_read_b128 v[34:37], v34 offset:17472
	ds_read_b128 v[42:45], v27 offset:64512
	ds_read_b128 v[46:49], v27 offset:64576
	v_lshl_add_u32 v38, s20, 1, v28
	s_waitcnt lgkmcnt(1)
	v_mfma_f32_16x16x32_bf16 v[30:33], v[30:33], v[42:45], 0
	s_waitcnt lgkmcnt(0)
	v_mfma_f32_16x16x32_bf16 v[30:33], v[34:37], v[46:49], v[30:33]
	s_nop 7
	v_cvt_pk_bf16_f32 v30, -v30, -v31
	v_cvt_pk_bf16_f32 v31, -v32, -v33
	ds_write_b64 v38, v[30:31]
	v_add3_u32 v29, s58, v29, v41
	s_cbranch_execz .LBB0_265

; __device__ __forceinline__ void st_bf4(bf16_t* p, f32x4 v) { u32x2 u; u.x = pk_bf16(v[0], v[1]); u.y = pk_bf16(v[2], v[3]); *(u32x2*)p = u; }
; #define MFMA16(a, b, c) __builtin_amdgcn_mfma_f32_16x16x32_bf16(a, b, c, 0, 0, 0)
; __device__ __forceinline__ void phase_prep(const Params& p, unsigned char* shm) {
;     ...
;                 } else { const int i2 = idx - 16, mt = i2 >> 2, nv = i2 & 3;
;                     c = MFMA16(ldfrag(Tm, LD, 16 * mt, 0, fr, fq), ldfrag(XT, LD, 16 * nv, 0, fr, fq), c);
;                     c = MFMA16(ldfrag(Tm, LD, 16 * mt, 32, fr, fq), ldfrag(XT, LD, 16 * nv, 32, fr, fq), c);
;                     st_bf4(U0t + (16 * nv + fr) * LD + 16 * mt + 4 * fq, -c);
;                 }
.LBB0_259:
	s_and_b32 s20, s23, 0x7ffffff0
	s_sub_i32 s20, s20, 64
	v_or_b32_e32 v30, s20, v185
	v_mul_u32_u24_e32 v30, s50, v30
	v_add3_u32 v34, 0, v30, v40
	ds_read_b128 v[30:33], v34 offset:17408
	ds_read_b128 v[34:37], v34 offset:17472
	ds_read_b128 v[42:45], v27 offset:64512
	ds_read_b128 v[46:49], v27 offset:64576
	v_lshl_add_u32 v38, s20, 1, v28
	s_waitcnt lgkmcnt(1)
	v_mfma_f32_16x16x32_bf16 v[30:33], v[30:33], v[42:45], 0
	s_waitcnt lgkmcnt(0)
	v_mfma_f32_16x16x32_bf16 v[30:33], v[34:37], v[46:49], v[30:33]
	s_nop 7
	v_cvt_pk_bf16_f32 v30, -v30, -v31
	v_cvt_pk_bf16_f32 v31, -v32, -v33
	ds_write_b64 v38, v[30:31]
	s_cbranch_execz .LBB0_267

; __device__ __forceinline__ void st_bf4(bf16_t* p, f32x4 v) { u32x2 u; u.x = pk_bf16(v[0], v[1]); u.y = pk_bf16(v[2], v[3]); *(u32x2*)p = u; }
; #define MFMA16(a, b, c) __builtin_amdgcn_mfma_f32_16x16x32_bf16(a, b, c, 0, 0, 0)
; __device__ __forceinline__ void phase_prep(const Params& p, unsigned char* shm) {
;     ...
;                 } else { const int i2 = idx - 16, mt = i2 >> 2, nv = i2 & 3;
;                     c = MFMA16(ldfrag(Tm, LD, 16 * mt, 0, fr, fq), ldfrag(XT, LD, 16 * nv, 0, fr, fq), c);
;                     c = MFMA16(ldfrag(Tm, LD, 16 * mt, 32, fr, fq), ldfrag(XT, LD, 16 * nv, 32, fr, fq), c);
;                     st_bf4(U0t + (16 * nv + fr) * LD + 16 * mt + 4 * fq, -c);
;                 }
.LBB0_263:
	s_and_b32 s20, s22, 0x7ffffff0
	s_sub_i32 s20, s20, 64
	v_or_b32_e32 v30, s20, v185
	v_mul_u32_u24_e32 v30, s50, v30
	v_add3_u32 v34, 0, v30, v40
	ds_read_b128 v[30:33], v34 offset:17408
	ds_read_b128 v[34:37], v34 offset:17472
	ds_read_b128 v[42:45], v27 offset:64512
	ds_read_b128 v[46:49], v27 offset:64576
	v_lshl_add_u32 v28, s20, 1, v28
	s_waitcnt lgkmcnt(1)
	v_mfma_f32_16x16x32_bf16 v[30:33], v[30:33], v[42:45], 0
	s_waitcnt lgkmcnt(0)
	v_mfma_f32_16x16x32_bf16 v[30:33], v[34:37], v[46:49], v[30:33]
	s_nop 7
	v_cvt_pk_bf16_f32 v30, -v30, -v31
	v_cvt_pk_bf16_f32 v31, -v32, -v33
	ds_write_b64 v28, v[30:31]
	s_cbranch_execnz .LBB0_177
	s_branch .LBB0_271

; __device__ __forceinline__ void st_bf4(bf16_t* p, f32x4 v) { u32x2 u; u.x = pk_bf16(v[0], v[1]); u.y = pk_bf16(v[2], v[3]); *(u32x2*)p = u; }
; #define MFMA16(a, b, c) __builtin_amdgcn_mfma_f32_16x16x32_bf16(a, b, c, 0, 0, 0)
; __device__ __forceinline__ void phase_prep(const Params& p, unsigned char* shm) {
;     ...
;                 if (idx < 16) { const int mk = idx >> 2, nt = idx & 3;
;                     c = MFMA16(ldfrag(KKtT, LD, 16 * mk, 0, fr, fq), ldfrag(Tm, LD, 16 * nt, 0, fr, fq), c);
;                     c = MFMA16(ldfrag(KKtT, LD, 16 * mk, 32, fr, fq), ldfrag(Tm, LD, 16 * nt, 32, fr, fq), c);
;                     st_bf4(W1t + (16 * nt + fr) * LD + 16 * mk + 4 * fq, -c);
.LBB0_265:
	s_and_b32 s20, s22, -16
	v_or_b32_e32 v30, s20, v185
	v_mul_u32_u24_e32 v30, s50, v30
	v_add3_u32 v34, s55, v30, v40
	ds_read_b128 v[30:33], v34
	ds_read_b128 v[34:37], v34 offset:64
	ds_read_b128 v[42:45], v27 offset:17408
	ds_read_b128 v[46:49], v27 offset:17472
	v_lshl_add_u32 v38, s20, 1, v29
	s_waitcnt lgkmcnt(1)
	v_mfma_f32_16x16x32_bf16 v[30:33], v[30:33], v[42:45], 0
	s_waitcnt lgkmcnt(0)
	v_mfma_f32_16x16x32_bf16 v[30:33], v[34:37], v[46:49], v[30:33]
	s_nop 7
	v_cvt_pk_bf16_f32 v30, -v30, -v31
	v_cvt_pk_bf16_f32 v31, -v32, -v33
	ds_write_b64 v38, v[30:31]
	s_add_i32 s23, s22, 32
	s_cmp_lt_i32 s71, 8
	s_mov_b64 s[20:21], -1
	s_cbranch_scc0 .LBB0_259

; __device__ __forceinline__ void st_bf4(bf16_t* p, f32x4 v) { u32x2 u; u.x = pk_bf16(v[0], v[1]); u.y = pk_bf16(v[2], v[3]); *(u32x2*)p = u; }
; #define MFMA16(a, b, c) __builtin_amdgcn_mfma_f32_16x16x32_bf16(a, b, c, 0, 0, 0)
; __device__ __forceinline__ void phase_prep(const Params& p, unsigned char* shm) {
;     ...
;                 if (idx < 16) { const int mk = idx >> 2, nt = idx & 3;
;                     c = MFMA16(ldfrag(KKtT, LD, 16 * mk, 0, fr, fq), ldfrag(Tm, LD, 16 * nt, 0, fr, fq), c);
;                     c = MFMA16(ldfrag(KKtT, LD, 16 * mk, 32, fr, fq), ldfrag(Tm, LD, 16 * nt, 32, fr, fq), c);
;                     st_bf4(W1t + (16 * nt + fr) * LD + 16 * mk + 4 * fq, -c);
.LBB0_267:
	s_and_b32 s20, s23, -16
	v_or_b32_e32 v30, s20, v185
	v_mul_u32_u24_e32 v30, s50, v30
	v_add3_u32 v34, s55, v30, v40
	ds_read_b128 v[30:33], v34
	ds_read_b128 v[34:37], v34 offset:64
	ds_read_b128 v[42:45], v27 offset:17408
	ds_read_b128 v[46:49], v27 offset:17472
	v_lshl_add_u32 v38, s20, 1, v29
	s_waitcnt lgkmcnt(1)
	v_mfma_f32_16x16x32_bf16 v[30:33], v[30:33], v[42:45], 0
	s_waitcnt lgkmcnt(0)
	v_mfma_f32_16x16x32_bf16 v[30:33], v[34:37], v[46:49], v[30:33]
	s_nop 7
	v_cvt_pk_bf16_f32 v30, -v30, -v31
	v_cvt_pk_bf16_f32 v31, -v32, -v33
	ds_write_b64 v38, v[30:31]
	s_add_i32 s23, s22, 64
	s_cmp_lt_i32 s71, 0
	s_mov_b64 s[20:21], -1
	s_cbranch_scc0 .LBB0_261

; __device__ __forceinline__ void st_bf4(bf16_t* p, f32x4 v) { u32x2 u; u.x = pk_bf16(v[0], v[1]); u.y = pk_bf16(v[2], v[3]); *(u32x2*)p = u; }
; #define MFMA16(a, b, c) __builtin_amdgcn_mfma_f32_16x16x32_bf16(a, b, c, 0, 0, 0)
; __device__ __forceinline__ void phase_prep(const Params& p, unsigned char* shm) {
;     ...
;                 if (idx < 16) { const int mk = idx >> 2, nt = idx & 3;
;                     c = MFMA16(ldfrag(KKtT, LD, 16 * mk, 0, fr, fq), ldfrag(Tm, LD, 16 * nt, 0, fr, fq), c);
;                     c = MFMA16(ldfrag(KKtT, LD, 16 * mk, 32, fr, fq), ldfrag(Tm, LD, 16 * nt, 32, fr, fq), c);
;                     st_bf4(W1t + (16 * nt + fr) * LD + 16 * mk + 4 * fq, -c);
.LBB0_269:
	s_and_b32 s20, s23, -16
	v_or_b32_e32 v30, s20, v185
	v_mul_u32_u24_e32 v30, s50, v30
	v_add3_u32 v34, s55, v30, v40
	ds_read_b128 v[30:33], v34
	ds_read_b128 v[34:37], v34 offset:64
	ds_read_b128 v[42:45], v27 offset:17408
	ds_read_b128 v[46:49], v27 offset:17472
	v_lshl_add_u32 v38, s20, 1, v29
	s_waitcnt lgkmcnt(1)
	v_mfma_f32_16x16x32_bf16 v[30:33], v[30:33], v[42:45], 0
	s_waitcnt lgkmcnt(0)
	v_mfma_f32_16x16x32_bf16 v[30:33], v[34:37], v[46:49], v[30:33]
	s_nop 7
	v_cvt_pk_bf16_f32 v30, -v30, -v31
	v_cvt_pk_bf16_f32 v31, -v32, -v33
	ds_write_b64 v38, v[30:31]
	s_addk_i32 s22, 0x60
	s_cmp_lt_i32 s71, -8
	s_mov_b64 s[20:21], -1
	s_cbranch_scc0 .LBB0_263

; __device__ __forceinline__ void st_bf4(bf16_t* p, f32x4 v) { u32x2 u; u.x = pk_bf16(v[0], v[1]); u.y = pk_bf16(v[2], v[3]); *(u32x2*)p = u; }
; #define MFMA16(a, b, c) __builtin_amdgcn_mfma_f32_16x16x32_bf16(a, b, c, 0, 0, 0)
; __device__ __forceinline__ void phase_prep(const Params& p, unsigned char* shm) {
;     ...
;                 if (idx < 16) { const int mk = idx >> 2, nt = idx & 3;
;                     c = MFMA16(ldfrag(KKtT, LD, 16 * mk, 0, fr, fq), ldfrag(Tm, LD, 16 * nt, 0, fr, fq), c);
;                     c = MFMA16(ldfrag(KKtT, LD, 16 * mk, 32, fr, fq), ldfrag(Tm, LD, 16 * nt, 32, fr, fq), c);
;                     st_bf4(W1t + (16 * nt + fr) * LD + 16 * mk + 4 * fq, -c);
.LBB0_271:
	s_and_b32 s20, s22, -16
	v_or_b32_e32 v28, s20, v185
	v_mul_u32_u24_e32 v28, s50, v28
	v_add3_u32 v28, s55, v28, v40
	ds_read_b128 v[30:33], v28
	ds_read_b128 v[34:37], v28 offset:64
	ds_read_b128 v[38:41], v27 offset:17408
	ds_read_b128 v[42:45], v27 offset:17472
	v_lshl_add_u32 v27, s20, 1, v29
	s_waitcnt lgkmcnt(1)
	v_mfma_f32_16x16x32_bf16 v[30:33], v[30:33], v[38:41], 0
	s_waitcnt lgkmcnt(0)
	v_mfma_f32_16x16x32_bf16 v[28:31], v[34:37], v[42:45], v[30:33]
	s_nop 7
	v_cvt_pk_bf16_f32 v28, -v28, -v29
	v_cvt_pk_bf16_f32 v29, -v30, -v31
	ds_write_b64 v27, v[28:29]
	s_branch .LBB0_177
